# speedup vs baseline: 1.0635x; 1.0014x over previous
; DI int ltid() { int x = threadIdx.x; asm volatile("" : "+v"(x)); return x; }
; DI int fetch_task(unsigned* ctr, char* smem) {
;   unsigned* slot = (unsigned*)(smem + SM_TASK);
;   __syncthreads();
;   if (ltid() == 0) *slot = atomicAdd(ctr, 1u);
;   __syncthreads();
;   return (int)*slot;
; }
; DI void dil1_attn_phase(const Params& p, char* smem) {
;     ...
;     const int task = fetch_task(p.ctr + 4, smem);
;     if (task >= 1024) break;
;     const int tid = ltid(), lane = tid & 63, wid = tid >> 6, r = lane & 31, h = lane >> 5;
;     const int half = task & 1, hg = (task >> 1) & 3, b = (task >> 3) & 1, qb128 = task >> 4;
;     const int q0 = qb128 * 128 + wid * 32, pos = q0 + r;
;     const long tok = (long)b * SEQ + pos;
;     f32x16 ot[4];
;     float m = 0.f, l = 0.f;
; #pragma unroll
;     for (int dc = 0; dc < 4; ++dc)
; #pragma unroll
;       for (int i = 0; i < 16; ++i) ot[dc][i] = 0.f;
;     const float slope2 = exp2f(-8.f * (float)(hg + 1) / 12.f) * LOG2E;
;     bf16x8 qf[4];
;     load_q(qf, p.qkvz + tok * LD + hg * 64, h);
;     const u16* kb_ = p.qkvz + (long)b * SEQ * LD + 768 + hg * 64;
;     const u16* vb_ = p.qkvz + (long)b * SEQ * LD + 1536 + hg * 256 + half * 128;
;     const int g0 = qb128 * 128;
;     const int tlo = (g0 - 128) > 0 ? ((g0 - 128) >> 6) : 0, thi = ((g0 + 127) >> 6) + 1;
;     flash_pass<128, false, false>(smem, kb_, LD, vb_, LD, tlo, thi, nullptr, qf, pos, 1, 129, slope2, q0, q0 + 31, nullptr, 0.f, ot, m, l);
.LBB0_1991:
	s_or_b64 exec, exec, s[4:5]
	s_waitcnt vmcnt(0)
	v_readfirstlane_b32 s4, v2
	s_nop 1
	s_waitcnt lgkmcnt(0)
	v_readlane_b32 s100, v255, 2
	s_mul_i32 s101, s98, s99
	s_nop 0
	s_add_i32 s100, s100, s101
	v_mov_b32_e32 v0, s100
	ds_write_b32 v144, v0
.LBB0_1992:
	s_or_b64 exec, exec, s[0:1]
	s_waitcnt lgkmcnt(0)
	s_barrier
	ds_read_b32 v0, v144
	s_add_i32 s98, s98, 1
	s_movk_i32 s0, 0x3ff
	s_waitcnt lgkmcnt(0)
	v_cmp_lt_i32_e32 vcc, s0, v0
	v_readfirstlane_b32 s8, v0
	s_mov_b64 s[0:1], -1
	s_cbranch_vccnz .LBB0_1987
	v_mov_b32_e32 v0, v222
	s_lshl_b32 s0, s8, 3
	v_ashrrev_i32_e32 v2, 1, v0
	s_and_b32 s9, s0, 0xffffff80
	v_and_b32_e32 v2, 0xffffffe0, v2
	v_add_u32_e32 v151, s9, v2
	v_and_or_b32 v130, v0, 31, v151
	s_lshl_b32 s0, s8, 10
	s_and_b32 s10, s0, 0x2000
	v_ashrrev_i32_e32 v131, 31, v130
	v_lshl_add_u64 v[128:129], v[130:131], 0, s[10:11]
	v_mov_b64_e32 v[2:3], s[2:3]
	s_bfe_u32 s92, s8, 0x20001
	v_mad_u64_u32 v[2:3], s[0:1], v128, s33, v[2:3]
	v_bfe_u32 v150, v0, 5, 1
	v_mad_i32_i24 v3, v129, s33, v3
	s_lshl_b32 s0, s92, 7
	s_mov_b32 s1, s11
	v_lshl_add_u64 v[2:3], v[2:3], 0, s[0:1]
	v_lshlrev_b32_e32 v0, 4, v150
	v_lshl_add_u64 v[2:3], v[2:3], 0, v[0:1]
	global_load_dwordx4 v[112:115], v[2:3], off
	global_load_dwordx4 v[116:119], v[2:3], off offset:32
	global_load_dwordx4 v[120:123], v[2:3], off offset:64
	global_load_dwordx4 v[124:127], v[2:3], off offset:96
	s_and_b32 s93, s8, 1
	s_mul_i32 s1, s10, 0x1c00
	s_add_u32 s1, s2, s1
	s_addc_u32 s6, s3, 0
	s_add_u32 s4, s1, s0
	s_addc_u32 s5, s6, 0
	s_lshl_b32 s0, s92, 9
	s_add_u32 s0, s1, s0
	s_addc_u32 s1, s6, 0
	s_lshl_b32 s6, s93, 8
	s_add_u32 s6, s0, s6
	s_addc_u32 s7, s1, 0
	s_add_i32 s0, s9, 0xffffff80
	s_ashr_i32 s0, s0, 6
	s_cmpk_gt_i32 s9, 0x80
	s_cselect_b32 s10, s0, 0
	s_ashr_i32 s87, s8, 3
	s_or_b32 s86, s87, 1
	v_mov_b32_e32 v3, v222
	s_waitcnt lgkmcnt(0)
	s_cmp_lt_i32 s86, s10
	s_cselect_b64 s[8:9], -1, 0
	s_cmp_ge_i32 s86, s10
	v_and_b32_e32 v2, 63, v3
	v_ashrrev_i32_e32 v4, 6, v3
	s_cselect_b64 s[0:1], -1, 0
	s_and_b64 vcc, exec, s[8:9]
	s_barrier
	s_cbranch_vccnz .LBB0_1995
	v_lshrrev_b32_e32 v5, 3, v2
	s_lshl_b32 s94, s86, 6
	v_lshrrev_b32_e32 v11, 4, v2
	v_lshlrev_b32_e32 v10, 4, v4
	v_xor_b32_e32 v0, v11, v2
	v_or_b32_e32 v6, s94, v5
	v_add_u32_e32 v8, v6, v10
	v_mov_b64_e32 v[6:7], s[4:5]
	v_lshlrev_b32_e32 v0, 4, v0
	v_mad_i64_i32 v[8:9], s[88:89], v8, s33, v[6:7]
	v_and_b32_e32 v0, 0x70, v0
	v_lshlrev_b32_e32 v12, 11, v4
	v_lshl_add_u64 v[8:9], v[8:9], 0, v[0:1]
	v_readfirstlane_b32 s88, v12
	v_lshl_add_u64 v[8:9], v[8:9], 0, s[18:19]
	s_mov_b32 m0, s88
	v_or_b32_e32 v13, s94, v11
	global_load_lds_dwordx4 v[8:9], off
	v_lshl_or_b32 v8, v4, 1, 1
	v_lshl_or_b32 v0, v8, 3, v5
	v_lshrrev_b32_e32 v5, 1, v0
	v_xor_b32_e32 v5, v5, v3
	v_add_u32_e32 v0, s94, v0
	v_mad_i64_i32 v[6:7], s[88:89], v0, s33, v[6:7]
	v_lshlrev_b32_e32 v0, 4, v5
	v_and_b32_e32 v0, 0x70, v0
	v_lshl_add_u64 v[6:7], v[6:7], 0, v[0:1]
	v_lshlrev_b32_e32 v0, 10, v8
	v_lshl_add_u64 v[6:7], v[6:7], 0, s[18:19]
	v_readfirstlane_b32 s88, v0
	s_mov_b32 m0, s88
	v_lshlrev_b32_e32 v0, 4, v2
	global_load_lds_dwordx4 v[6:7], off
	v_lshlrev_b32_e32 v6, 6, v11
	v_bitop3_b32 v0, v6, v0, s56 bitop3:0x78
	v_lshl_add_u64 v[6:7], s[6:7], 0, v[0:1]
	v_add_u32_e32 v0, v13, v10
	v_mad_i64_i32 v[8:9], s[88:89], v0, s33, v[6:7]
	s_movk_i32 s88, 0x2000
	s_nop 0
	v_add3_u32 v0, v12, v12, s88
	v_lshlrev_b32_e32 v5, 2, v4
	v_readfirstlane_b32 s88, v0
	v_lshl_add_u64 v[8:9], v[8:9], 0, s[20:21]
	s_mov_b32 m0, s88
	v_or_b32_e32 v0, 1, v5
	global_load_lds_dwordx4 v[8:9], off
	v_lshl_add_u32 v8, v0, 2, v13
	v_mad_i64_i32 v[8:9], s[88:89], v8, s33, v[6:7]
	v_lshl_add_u32 v0, v0, 10, v145
	v_lshl_add_u64 v[8:9], v[8:9], 0, s[20:21]
	v_readfirstlane_b32 s88, v0
	s_mov_b32 m0, s88
	v_or_b32_e32 v0, 2, v5
	global_load_lds_dwordx4 v[8:9], off
	v_lshl_add_u32 v8, v0, 2, v13
	v_mad_i64_i32 v[8:9], s[88:89], v8, s33, v[6:7]
	v_lshl_add_u32 v0, v0, 10, v145
	v_lshl_add_u64 v[8:9], v[8:9], 0, s[20:21]
	v_readfirstlane_b32 s88, v0
	v_or_b32_e32 v0, 3, v5
	v_lshl_add_u32 v5, v0, 2, v13
	s_mov_b32 m0, s88
	v_mad_i64_i32 v[6:7], s[88:89], v5, s33, v[6:7]
	v_lshl_add_u32 v0, v0, 10, v145
	global_load_lds_dwordx4 v[8:9], off
	v_readfirstlane_b32 s88, v0
	v_lshl_add_u64 v[6:7], v[6:7], 0, s[20:21]
	s_mov_b32 m0, s88
	s_nop 0
	global_load_lds_dwordx4 v[6:7], off

; DI int ltid() { int x = threadIdx.x; asm volatile("" : "+v"(x)); return x; }
; DI int fetch_task(unsigned* ctr, char* smem) {
;   unsigned* slot = (unsigned*)(smem + SM_TASK);
;   __syncthreads();
;   if (ltid() == 0) *slot = atomicAdd(ctr, 1u);
;   __syncthreads();
;   return (int)*slot;
; }
; DI void dil_attn_phase(const Params& p, char* smem) {
;     ...
;     const int task = fetch_task(p.ctr + 2, smem);
;     if (task >= 1024) break;
;     const int tid = ltid(), lane = tid & 63, wid = tid >> 6, r = lane & 31, h = lane >> 5;
;     const int half = task & 1, hg = (task >> 1) & 3, b = (task >> 3) & 1, grp = task >> 4;
;     const int r16 = grp & 15, U0 = (grp >> 4) * 128;
;     const int u16q = U0 + wid * 32 + r;
;     const int pos = r16 + 16 * u16q;
;     const long tok = (long)b * SEQ + pos;
;     f32x16 ot[4];
;     float m = 0.f, l = 0.f;
; #pragma unroll
;     for (int dc = 0; dc < 4; ++dc)
; #pragma unroll
;       for (int i = 0; i < 16; ++i) ot[dc][i] = 0.f;
; #pragma unroll
;     for (int g = 1; g < 3; ++g) {
;       const int d = (g == 1) ? 4 : 16;
;       const int res = pos % d;
;       const int uq = pos / d;
;       const int wpos0 = r16 + 16 * (U0 + wid * 32), wpos1 = wpos0 + 16 * 31;
;       const int wq_min = wpos0 / d, wq_max = wpos1 / d;
;       const int gpos0 = r16 + 16 * U0, gpos1 = gpos0 + 16 * 127;
;       const int gq_min = gpos0 / d, gq_max = gpos1 / d;
;       const int tlo = (gq_min - 128) > 0 ? ((gq_min - 128) >> 6) : 0;
;       const int thi = (gq_max >> 6) + 1;
;       const float slope = exp2f(-8.f * (float)(4 * g + hg + 1) / 12.f);
;       const float slope2 = slope * (float)d * LOG2E;
;       bf16x8 qf[4];
;       load_q(qf, p.qkvz + tok * LD + g * 256 + hg * 64, h);
;       const u16* kb_ = p.qkvz + ((long)b * SEQ + res) * LD + 768 + g * 256 + hg * 64;
;       const u16* vb_ = p.qkvz + ((long)b * SEQ + res) * LD + 1536 + hg * 256 + half * 128;
;       flash_pass<128, false, false>(smem, kb_, LD * d, vb_, LD * d, tlo, thi, nullptr, qf, uq, 1, 129, slope2, wq_min, wq_max, nullptr, 0.f, ot, m, l);
.LBB0_2080:
	s_or_b64 exec, exec, s[4:5]
	s_waitcnt vmcnt(0)
	v_readfirstlane_b32 s4, v2
	s_nop 1
	s_waitcnt lgkmcnt(0)
	v_readlane_b32 s100, v255, 2
	s_mul_i32 s101, s98, s99
	s_nop 0
	s_add_i32 s100, s100, s101
	v_mov_b32_e32 v0, s100
	ds_write_b32 v148, v0
.LBB0_2081:
	s_or_b64 exec, exec, s[0:1]
	s_waitcnt lgkmcnt(0)
	s_barrier
	ds_read_b32 v0, v148
	s_add_i32 s98, s98, 1
	s_movk_i32 s0, 0x3ff
	s_waitcnt lgkmcnt(0)
	v_cmp_lt_i32_e32 vcc, s0, v0
	v_readfirstlane_b32 s4, v0
	s_mov_b64 s[0:1], -1
	s_cbranch_vccnz .LBB0_2076
	v_mov_b32_e32 v0, v222
	s_ashr_i32 s0, s4, 1
	v_ashrrev_i32_e32 v2, 1, v0
	s_and_b32 s0, s0, 0xffffff80
	v_and_b32_e32 v2, 0xffffffe0, v2
	s_lshl_b32 s1, s4, 10
	s_bfe_u32 s6, s4, 0x40004
	v_add_u32_e32 v9, s0, v2
	s_and_b32 s10, s1, 0x2000
	s_lshl_b32 s1, s0, 4
	s_bfe_i32 s0, s0, 0x1001b
	s_or_b32 s91, s1, s6
	s_lshr_b32 s0, s0, 30
	s_add_i32 s1, s91, s0
	v_and_or_b32 v6, v0, 31, v9
	s_ashr_i32 s1, s1, 2
	v_lshl_or_b32 v132, v6, 4, s6
	s_or_b32 s16, s91, 0x7f0
	s_addk_i32 s1, 0xff80
	v_readlane_b32 s92, v255, 14
	v_ashrrev_i32_e32 v133, 31, v132
	s_and_b32 s13, s4, 1
	s_bfe_u32 s14, s4, 0x20001
	s_add_i32 s7, s16, s0
	s_ashr_i32 s0, s1, 6
	v_readlane_b32 s94, v255, 16
	v_readlane_b32 s95, v255, 17
	v_lshl_add_u64 v[128:129], v[132:133], 0, s[10:11]
	s_cmpk_gt_i32 s91, 0x203
	v_mov_b64_e32 v[2:3], s[94:95]
	s_cselect_b32 s15, s0, 0
	v_mad_u64_u32 v[130:131], s[0:1], v128, s56, v[2:3]
	v_bfe_u32 v154, v0, 5, 1
	v_mad_i32_i24 v131, v129, s56, v131
	s_lshl_b32 s0, s14, 7
	s_mov_b32 s1, s11
	v_lshl_add_u64 v[4:5], v[130:131], 0, s[0:1]
	v_lshlrev_b32_e32 v0, 4, v154
	v_lshl_add_u64 v[134:135], v[4:5], 0, v[0:1]
	global_load_dwordx4 v[112:115], v[134:135], off offset:512
	global_load_dwordx4 v[116:119], v[134:135], off offset:544
	global_load_dwordx4 v[120:123], v[134:135], off offset:576
	global_load_dwordx4 v[124:127], v[134:135], off offset:608
	v_bfe_i32 v0, v6, 27, 1
	v_lshrrev_b32_e32 v0, 30, v0
	v_add_u32_e32 v10, v132, v0
	v_and_b32_e32 v0, -4, v10
	v_sub_u32_e32 v4, v132, v0
	v_ashrrev_i32_e32 v5, 31, v4
	v_lshl_add_u64 v[4:5], v[4:5], 0, s[10:11]
	v_mad_u64_u32 v[6:7], s[4:5], v4, s56, v[2:3]
	v_mad_i32_i24 v7, v5, s56, v7
	v_lshl_add_u64 v[2:3], v[6:7], 0, s[0:1]
	s_lshl_b32 s0, s14, 9
	s_ashr_i32 s8, s7, 8
	v_lshl_add_u64 v[4:5], v[6:7], 0, s[0:1]
	s_lshl_b32 s0, s13, 8
	v_mov_b32_e32 v7, v222
	s_waitcnt lgkmcnt(0)
	s_cmp_lt_i32 s8, s15
	s_cselect_b64 s[4:5], -1, 0
	s_cmp_ge_i32 s8, s15
	v_lshl_add_u64 v[4:5], v[4:5], 0, s[0:1]
	v_and_b32_e32 v6, 63, v7
	v_ashrrev_i32_e32 v8, 6, v7
	s_cselect_b64 s[0:1], -1, 0
	s_and_b64 vcc, exec, s[4:5]
	v_readlane_b32 s93, v255, 15
	s_barrier
	s_cbranch_vccnz .LBB0_2084
	s_ashr_i32 s7, s7, 2
	v_lshrrev_b32_e32 v11, 3, v6
	s_andn2_b32 s7, s7, 63
	v_lshrrev_b32_e32 v15, 4, v6
	v_lshlrev_b32_e32 v14, 4, v8
	v_xor_b32_e32 v0, v15, v6
	v_or_b32_e32 v12, s7, v11
	v_add_u32_e32 v12, v12, v14
	v_lshlrev_b32_e32 v0, 4, v0
	v_mad_i64_i32 v[12:13], s[18:19], v12, s57, v[2:3]
	v_and_b32_e32 v0, 0x70, v0
	v_lshl_or_b32 v17, v8, 1, 1
	v_lshl_add_u64 v[12:13], v[12:13], 0, v[0:1]
	v_lshlrev_b32_e32 v16, 11, v8
	v_lshl_or_b32 v0, v17, 3, v11
	v_readfirstlane_b32 s9, v16
	v_lshrrev_b32_e32 v11, 1, v0
	v_lshl_add_u64 v[12:13], v[12:13], 0, s[20:21]
	s_mov_b32 m0, s9
	v_xor_b32_e32 v11, v11, v7
	v_add_u32_e32 v0, s7, v0
	global_load_lds_dwordx4 v[12:13], off
	v_mad_i64_i32 v[12:13], s[18:19], v0, s57, v[2:3]
	v_lshlrev_b32_e32 v0, 4, v11
	v_and_b32_e32 v0, 0x70, v0
	v_lshl_add_u64 v[12:13], v[12:13], 0, v[0:1]
	v_lshlrev_b32_e32 v0, 10, v17
	v_lshl_add_u64 v[12:13], v[12:13], 0, s[20:21]
	v_readfirstlane_b32 s9, v0
	s_mov_b32 m0, s9
	v_or_b32_e32 v17, s7, v15
	global_load_lds_dwordx4 v[12:13], off
	v_lshlrev_b32_e32 v0, 4, v6
	v_lshlrev_b32_e32 v12, 6, v15
	s_movk_i32 s7, 0xf0
	v_bitop3_b32 v0, v12, v0, s7 bitop3:0x78
	v_lshl_add_u64 v[12:13], v[4:5], 0, v[0:1]
	v_add_u32_e32 v0, v17, v14
	v_mad_i64_i32 v[14:15], s[18:19], v0, s57, v[12:13]
	v_add3_u32 v0, v16, v16, s96
	v_lshlrev_b32_e32 v11, 2, v8
	v_readfirstlane_b32 s7, v0
	v_lshl_add_u64 v[14:15], v[14:15], 0, s[22:23]
	s_mov_b32 m0, s7
	v_or_b32_e32 v0, 1, v11
	global_load_lds_dwordx4 v[14:15], off
	v_lshl_add_u32 v14, v0, 2, v17
	v_lshl_add_u32 v0, v0, 10, v149
	v_mad_i64_i32 v[14:15], s[18:19], v14, s57, v[12:13]
	v_readfirstlane_b32 s7, v0
	v_lshl_add_u64 v[14:15], v[14:15], 0, s[22:23]
	s_mov_b32 m0, s7
	v_or_b32_e32 v0, 2, v11
	global_load_lds_dwordx4 v[14:15], off
	v_lshl_add_u32 v14, v0, 2, v17
	v_lshl_add_u32 v0, v0, 10, v149
	v_mad_i64_i32 v[14:15], s[18:19], v14, s57, v[12:13]
	v_readfirstlane_b32 s7, v0
	v_or_b32_e32 v0, 3, v11
	v_lshl_add_u32 v11, v0, 2, v17
	v_lshl_add_u32 v0, v0, 10, v149
	v_lshl_add_u64 v[14:15], v[14:15], 0, s[22:23]
	s_mov_b32 m0, s7
	v_mad_i64_i32 v[12:13], s[18:19], v11, s57, v[12:13]
	v_readfirstlane_b32 s7, v0
	global_load_lds_dwordx4 v[14:15], off
	v_lshl_add_u64 v[12:13], v[12:13], 0, s[22:23]
	s_mov_b32 m0, s7
	s_nop 0
	global_load_lds_dwordx4 v[12:13], off

; DI int ltid() { int x = threadIdx.x; asm volatile("" : "+v"(x)); return x; }
; #define RAW_BARRIER() do { asm volatile("s_waitcnt lgkmcnt(0)" ::: "memory"); __builtin_amdgcn_s_barrier(); } while (0)
; DI int fetch_task(unsigned* ctr, char* smem) {
;   unsigned* slot = (unsigned*)(smem + SM_TASK);
;   __syncthreads();
;   if (ltid() == 0) *slot = atomicAdd(ctr, 1u);
;   __syncthreads();
;   return (int)*slot;
; }
; DI void stick_attn_phase(const Params& p, char* smem) {
;     ...
;     const int task = fetch_task(p.ctr + 3, smem);
;     if (task >= 2048) break;
;     const int tid = ltid(), lane = tid & 63, wid = tid >> 6, r = lane & 31, h = lane >> 5;
;     const int qt = 63 - (task >> 5), bh = task & 31, b = bh >> 4, hd = bh & 15;
;     const int q0 = qt * 128 + wid * 32, tq = q0 + r;
;     const long tok = (long)b * SEQ + tq;
;     bf16x8 qf[4];
;     load_q(qf, p.qkvz + tok * LD + hd * 64, h);
;     const u16* kb_ = p.qkvz + (long)b * SEQ * LD + 1024 + hd * 64;
;     const u16* vb_ = p.qkvz + (long)b * SEQ * LD + 2048 + hd * 64;
;     f32x16 ot[2];
; #pragma unroll
;     for (int dc = 0; dc < 2; ++dc)
; #pragma unroll
;       for (int i = 0; i < 16; ++i) ot[dc][i] = 0.f;
;     float carry = 0.f;
;     unsigned done = 0u;
;     int foff[4];
;     make_foff(foff, r, h);
;     RAW_BARRIER();
;     int t = ((qt * 128 + 127) >> 6);
;     kv_issue<64, true>(smem, 0, kb_, LD, vb_, LD, t, lane, wid);
;     if (t >= 1) kv_issue<64, true>(smem, 1, kb_, LD, vb_, LD, t - 1, lane, wid);
;     int c = 0;
.LBB0_2603:
	s_or_b64 exec, exec, s[4:5]
	s_waitcnt vmcnt(0)
	v_readfirstlane_b32 s4, v2
	s_nop 1
	s_waitcnt lgkmcnt(0)
	v_readlane_b32 s100, v255, 2
	s_mul_i32 s101, s98, s99
	s_nop 0
	s_add_i32 s100, s100, s101
	v_mov_b32_e32 v0, s100
	ds_write_b32 v110, v0
.LBB0_2604:
	s_or_b64 exec, exec, s[0:1]
	s_waitcnt lgkmcnt(0)
	s_barrier
	ds_read_b32 v0, v110
	s_add_i32 s98, s98, 1
	s_mov_b64 s[0:1], -1
	s_waitcnt lgkmcnt(0)
	v_cmp_lt_i32_e32 vcc, s28, v0
	v_readfirstlane_b32 s4, v0
	s_cbranch_vccnz .LBB0_2599
	v_mov_b32_e32 v6, v222
	s_lshl_b32 s0, s4, 2
	v_ashrrev_i32_e32 v7, 6, v6
	s_and_b32 s8, s0, 0xffffff80
	v_lshlrev_b32_e32 v0, 5, v7
	v_subrev_u32_e32 v10, s8, v0
	v_and_b32_e32 v8, 31, v6
	v_add_u32_e32 v113, 0x1f80, v10
	v_or_b32_e32 v98, v113, v8
	s_lshl_b32 s0, s4, 9
	s_and_b32 s18, s0, 0x2000
	v_ashrrev_i32_e32 v99, 31, v98
	v_lshl_add_u64 v[96:97], v[98:99], 0, s[18:19]
	s_lshl_b32 s0, s4, 6
	v_lshlrev_b64 v[2:3], 13, v[96:97]
	s_and_b32 s31, s0, 0x3c0
	v_lshl_add_u64 v[100:101], s[14:15], 0, v[2:3]
	s_lshl_b32 s0, s31, 1
	s_mov_b32 s1, s19
	v_lshl_add_u64 v[2:3], v[100:101], 0, s[0:1]
	s_lshl_b32 s1, s18, 13
	s_add_u32 s1, s14, s1
	v_bfe_u32 v9, v6, 5, 1
	s_addc_u32 s4, s15, 0
	v_lshlrev_b32_e32 v0, 4, v9
	s_add_u32 s0, s1, s0
	v_bfe_u32 v11, v6, 3, 3
	v_lshlrev_b32_e32 v12, 4, v7
	v_lshl_add_u64 v[2:3], v[2:3], 0, v[0:1]
	s_addc_u32 s1, s4, 0
	s_sub_i32 s4, 0x1fc0, s8
	v_or_b32_e32 v99, v12, v11
	global_load_dwordx4 v[80:83], v[2:3], off
	global_load_dwordx4 v[84:87], v[2:3], off offset:32
	global_load_dwordx4 v[88:91], v[2:3], off offset:64
	global_load_dwordx4 v[92:95], v[2:3], off offset:96
	v_bfe_u32 v0, v6, 4, 2
	v_add_u32_e32 v2, s4, v99
	v_xor_b32_e32 v0, v0, v6
	v_ashrrev_i32_e32 v3, 31, v2
	v_lshlrev_b64 v[2:3], 13, v[2:3]
	v_lshlrev_b32_e32 v0, 4, v0
	v_lshl_add_u64 v[2:3], s[0:1], 0, v[2:3]
	v_and_b32_e32 v0, 0x70, v0
	v_lshlrev_b32_e32 v13, 11, v7
	v_lshl_or_b32 v14, v7, 1, 1
	v_lshl_add_u64 v[2:3], v[2:3], 0, v[0:1]
	v_readfirstlane_b32 s5, v13
	v_lshlrev_b32_e32 v15, 3, v14
	v_lshl_add_u64 v[2:3], v[2:3], 0, s[20:21]
	s_mov_b32 m0, s5
	v_or_b32_e32 v16, v15, v11
	s_waitcnt lgkmcnt(0)
	s_barrier
	global_load_lds_dwordx4 v[2:3], off
	v_lshrrev_b32_e32 v2, 1, v16
	v_xor_b32_e32 v4, v2, v6
	v_add_u32_e32 v2, s4, v16
	v_ashrrev_i32_e32 v3, 31, v2
	v_lshlrev_b64 v[2:3], 13, v[2:3]
	v_lshlrev_b32_e32 v4, 4, v4
	v_lshl_add_u64 v[2:3], s[0:1], 0, v[2:3]
	v_and_b32_e32 v4, 0x70, v4
	v_mov_b32_e32 v5, v1
	v_lshlrev_b32_e32 v14, 10, v14
	v_lshl_add_u64 v[2:3], v[2:3], 0, v[4:5]
	v_readfirstlane_b32 s5, v14
	v_lshl_add_u64 v[2:3], v[2:3], 0, s[20:21]
	s_mov_b32 m0, s5
	v_or_b32_e32 v17, s4, v11
	global_load_lds_dwordx4 v[2:3], off
	v_and_b32_e32 v2, 7, v6
	v_bfe_u32 v3, v6, 2, 4
	v_bitop3_b32 v2, v3, v2, 4 bitop3:0x6c
	v_lshlrev_b32_e32 v2, 4, v2
	v_mov_b32_e32 v3, v1
	v_lshl_add_u64 v[2:3], s[0:1], 0, v[2:3]
	v_lshl_add_u64 v[102:103], v[2:3], 0, s[22:23]
	v_add_u32_e32 v2, v17, v12
	v_ashrrev_i32_e32 v3, 31, v2
	v_add_u32_e32 v18, 0x2000, v13
	v_lshlrev_b64 v[2:3], 13, v[2:3]
	v_readfirstlane_b32 s5, v18
	v_lshl_add_u64 v[2:3], v[102:103], 0, v[2:3]
	s_mov_b32 m0, s5
	v_lshl_add_u64 v[106:107], s[0:1], 0, v[4:5]
	global_load_lds_dwordx4 v[2:3], off
	v_add_u32_e32 v2, v15, v17
	v_ashrrev_i32_e32 v3, 31, v2
	v_add_u32_e32 v17, 0x2000, v14
	v_lshlrev_b64 v[2:3], 13, v[2:3]
	v_readfirstlane_b32 s5, v17
	v_lshl_add_u64 v[2:3], v[102:103], 0, v[2:3]
	s_mov_b32 m0, s5
	s_sub_i32 s5, 0x1f80, s8
	global_load_lds_dwordx4 v[2:3], off
	v_add_u32_e32 v2, s5, v99
	v_ashrrev_i32_e32 v3, 31, v2
	v_lshlrev_b64 v[2:3], 13, v[2:3]
	v_lshl_add_u64 v[2:3], s[0:1], 0, v[2:3]
	v_add_u32_e32 v17, 0x4000, v13
	v_lshl_add_u64 v[2:3], v[2:3], 0, v[0:1]
	v_readfirstlane_b32 s6, v17
	v_lshl_add_u64 v[2:3], v[2:3], 0, s[20:21]
	s_mov_b32 m0, s6
	s_lshr_b32 s33, s4, 6
	global_load_lds_dwordx4 v[2:3], off
	v_add_u32_e32 v2, s5, v16
	v_ashrrev_i32_e32 v3, 31, v2
	v_lshlrev_b64 v[2:3], 13, v[2:3]
	v_lshl_add_u64 v[2:3], s[0:1], 0, v[2:3]
	v_add_u32_e32 v16, 0x4000, v14
	v_lshl_add_u64 v[2:3], v[2:3], 0, v[4:5]
	v_readfirstlane_b32 s6, v16
	v_lshl_add_u64 v[2:3], v[2:3], 0, s[20:21]
	s_mov_b32 m0, s6
	v_or_b32_e32 v16, s5, v11
	global_load_lds_dwordx4 v[2:3], off
	v_add_u32_e32 v2, v16, v12
	v_ashrrev_i32_e32 v3, 31, v2
	v_add_u32_e32 v12, 0x6000, v13
	v_lshlrev_b64 v[2:3], 13, v[2:3]
	v_readfirstlane_b32 s5, v12
	v_lshl_add_u64 v[2:3], v[102:103], 0, v[2:3]
	s_mov_b32 m0, s5
	v_add_u32_e32 v12, 0x6000, v14
	global_load_lds_dwordx4 v[2:3], off
	v_add_u32_e32 v2, v15, v16
	v_ashrrev_i32_e32 v3, 31, v2
	v_lshlrev_b64 v[2:3], 13, v[2:3]
	v_readfirstlane_b32 s5, v12
	v_lshl_add_u64 v[2:3], v[102:103], 0, v[2:3]
	s_mov_b32 m0, s5
	v_bfe_u32 v12, v6, 1, 3
	global_load_lds_dwordx4 v[2:3], off
	v_and_b32_e32 v2, 63, v6
	v_lshlrev_b32_e32 v4, 1, v6
	v_lshlrev_b32_e32 v3, 7, v8
	v_lshrrev_b32_e32 v8, 1, v6
	v_bitop3_b32 v14, v9, v12, 2 bitop3:0x36
	v_bitop3_b32 v15, v9, v12, 4 bitop3:0x36
	v_lshl_add_u64 v[104:105], s[0:1], 0, v[0:1]
	v_cmp_eq_u32_e64 s[4:5], 0, v2
	v_cmp_gt_u32_e64 s[6:7], 32, v2
	v_bfe_u32 v0, v2, 2, 2
	v_and_b32_e32 v4, 32, v4
	v_lshlrev_b32_e32 v2, 3, v2
	v_bitop3_b32 v8, v9, v8, 7 bitop3:0x78
	v_bitop3_b32 v12, v9, v12, 6 bitop3:0x36
	v_and_or_b32 v0, v11, 4, v0
	v_and_or_b32 v4, v2, 24, v4
	v_lshl_or_b32 v125, v15, 4, v3
	v_lshl_or_b32 v127, v14, 4, v3
	v_mov_b32_e32 v14, v1
	v_mov_b32_e32 v15, v1
	v_lshl_add_u32 v114, v7, 2, v111
	v_add_u32_e32 v116, 0x1f9f, v10
	v_lshlrev_b32_e32 v115, 2, v9
	v_lshl_or_b32 v117, v0, 7, v4
	v_and_b32_e32 v118, 64, v2
	v_bitop3_b32 v119, v2, 64, v2 bitop3:0xc
	v_add_u32_e32 v120, 0xa400, v13
	v_add_u32_e32 v121, 0x8400, v13
	v_add_u32_e32 v122, 0xa000, v13
	v_add_u32_e32 v123, 0x8000, v13
	v_lshl_or_b32 v124, v12, 4, v3
	v_lshl_or_b32 v126, v8, 4, v3
	v_mov_b32_e32 v0, v1
	v_mov_b32_e32 v2, v1
	v_mov_b32_e32 v3, v1
	v_mov_b32_e32 v4, v1
	v_mov_b32_e32 v6, v1
	v_mov_b32_e32 v7, v1
	v_mov_b32_e32 v8, v1
	v_mov_b32_e32 v9, v1
	v_mov_b32_e32 v10, v1
	v_mov_b32_e32 v11, v1
	v_mov_b32_e32 v12, v1
	v_mov_b32_e32 v13, v1
	v_mov_b64_e32 v[30:31], v[14:15]
	v_mov_b64_e32 v[46:47], v[14:15]
	s_mov_b32 s18, 2
	s_mov_b32 s34, 0
	s_sub_i32 s35, 0x1fff, s8
	v_mov_b32_e32 v109, 0
	v_mov_b32_e32 v48, 0
	s_mov_b32 s36, 0
	v_mov_b64_e32 v[28:29], v[12:13]
	v_mov_b64_e32 v[26:27], v[10:11]
	v_mov_b64_e32 v[24:25], v[8:9]
	v_mov_b64_e32 v[22:23], v[6:7]
	v_mov_b64_e32 v[20:21], v[4:5]
	v_mov_b64_e32 v[18:19], v[2:3]
	v_mov_b64_e32 v[16:17], v[0:1]
	s_mov_b32 s37, 0
	v_mov_b64_e32 v[44:45], v[12:13]
	v_mov_b64_e32 v[42:43], v[10:11]
	v_mov_b64_e32 v[40:41], v[8:9]
	v_mov_b64_e32 v[38:39], v[6:7]
	v_mov_b64_e32 v[36:37], v[4:5]
	v_mov_b64_e32 v[34:35], v[2:3]
	v_mov_b64_e32 v[32:33], v[0:1]
	s_waitcnt vmcnt(0)
	s_branch .LBB0_2607
